# fox_cumsum: the eight strided forget-logit loads per thread issued together (was load + vmcnt(0) x8)
# baseline (speedup 1.0000x reference)
; __device__ __forceinline__ float bf1(bf16_t h) { return __uint_as_float(((unsigned)h) << 16); }
; __device__ __forceinline__ void fox_cumsum(const bf16_t* PROJ, const float* bforget, float* Carr, LAS unsigned char* lds, int bid, int G, int tid) {
;     ...
;         const bf16_t* src = PROJ + ((size_t)b * SEQ + 8 * tid) * NP + C_FB + h;
;         float lf[8], loc = 0.f;
; #pragma unroll
;         for (int i = 0; i < 8; ++i) { const float x = bf1(src[(size_t)i * NP]) + bf; lf[i] = fminf(x, 0.f) - __logf(1.f + __expf(-fabsf(x))); loc += lf[i]; }
.LBB0_371:
	s_and_b32 s9, s36, 3
	s_ashr_i32 s4, s36, 2
	s_lshl_b32 s5, s9, 2
	v_mov_b32_e32 v6, s5
	s_ashr_i32 s5, s4, 31
	s_lshl_b64 s[4:5], s[4:5], 12
	global_load_dword v18, v6, s[34:35]
	v_lshl_add_u64 v[6:7], s[4:5], 0, v[2:3]
	v_mov_b64_e32 v[20:21], s[30:31]
	v_mad_u64_u32 v[20:21], s[4:5], v6, s88, v[20:21]
	v_mad_i32_i24 v21, v7, s88, v21
	s_lshl_b32 s94, s9, 1
	v_lshl_add_u64 v[6:7], v[20:21], 0, s[94:95]
	s_mov_b32 s4, 0xc702000
	v_add_co_u32_e64 v20, s[54:55], s4, v6
	s_mov_b32 s4, 0xc708000
	s_nop 0
	v_addc_co_u32_e64 v21, s[54:55], 0, v7, s[54:55]
	s_mov_b32 s101, 0
	s_mov_b32 s100, 0xc702a40
	v_lshl_add_u64 v[88:89], v[6:7], 0, s[100:101]
	global_load_ushort v80, v[88:89], off
	s_mov_b32 s100, 0xc708640
	v_lshl_add_u64 v[90:91], v[6:7], 0, s[100:101]
	global_load_ushort v81, v[90:91], off
	s_mov_b32 s100, 0xc70e240
	v_lshl_add_u64 v[92:93], v[6:7], 0, s[100:101]
	global_load_ushort v82, v[92:93], off
	s_mov_b32 s100, 0xc713e40
	v_lshl_add_u64 v[94:95], v[6:7], 0, s[100:101]
	global_load_ushort v83, v[94:95], off
	s_mov_b32 s100, 0xc719a40
	v_lshl_add_u64 v[96:97], v[6:7], 0, s[100:101]
	global_load_ushort v84, v[96:97], off
	s_mov_b32 s100, 0xc71f640
	v_lshl_add_u64 v[98:99], v[6:7], 0, s[100:101]
	global_load_ushort v85, v[98:99], off
	s_mov_b32 s100, 0xc725240
	v_lshl_add_u64 v[100:101], v[6:7], 0, s[100:101]
	global_load_ushort v86, v[100:101], off
	s_mov_b32 s100, 0xc72ae40
	v_lshl_add_u64 v[102:103], v[6:7], 0, s[100:101]
	global_load_ushort v87, v[102:103], off
	s_waitcnt vmcnt(0)
	v_mov_b32_e32 v17, v80
	v_lshlrev_b32_e32 v17, 16, v17
	v_add_f32_e32 v17, v18, v17
	v_min_f32_e32 v19, 0, v17
	v_mul_f32_e64 v17, |v17|, s89
	v_exp_f32_e32 v17, v17
	s_nop 0
	v_add_f32_e32 v17, 1.0, v17
	v_cmp_gt_f32_e64 s[54:55], s20, v17
	s_nop 1
	v_cndmask_b32_e64 v20, 0, 32, s[54:55]
	v_ldexp_f32 v17, v17, v20
	v_log_f32_e32 v17, v17
	s_nop 0
	v_mul_f32_e32 v20, 0x3f317217, v17
	v_fma_f32 v20, v17, s21, -v20
	v_fmac_f32_e32 v20, 0x3377d1cf, v17
	v_fmac_f32_e32 v20, 0x3f317217, v17
	v_cmp_lt_f32_e64 s[56:57], |v17|, s8
	s_nop 1
	v_cndmask_b32_e64 v17, v17, v20, s[56:57]
	v_cndmask_b32_e64 v20, 0, v217, s[54:55]
	v_sub_f32_e32 v17, v17, v20
	v_add_co_u32_e64 v20, s[54:55], s4, v6
	v_sub_f32_e32 v17, v19, v17
	s_nop 0
	v_addc_co_u32_e64 v21, s[54:55], 0, v7, s[54:55]
	v_mov_b32_e32 v19, v81
	s_mov_b32 s4, 0xc70e000
	v_add_f32_e32 v22, 0, v17
	s_waitcnt vmcnt(0)
	v_lshlrev_b32_e32 v19, 16, v19
	v_add_f32_e32 v19, v18, v19
	v_min_f32_e32 v20, 0, v19
	v_mul_f32_e64 v19, |v19|, s89
	v_exp_f32_e32 v19, v19
	s_nop 0
	v_add_f32_e32 v19, 1.0, v19
	v_cmp_gt_f32_e64 s[54:55], s20, v19
	s_nop 1
	v_cndmask_b32_e64 v21, 0, 32, s[54:55]
	v_ldexp_f32 v19, v19, v21
	v_log_f32_e32 v19, v19
	s_nop 0
	v_mul_f32_e32 v21, 0x3f317217, v19
	v_fma_f32 v21, v19, s21, -v21
	v_fmac_f32_e32 v21, 0x3377d1cf, v19
	v_fmac_f32_e32 v21, 0x3f317217, v19
	v_cmp_lt_f32_e64 s[56:57], |v19|, s8
	s_nop 1
	v_cndmask_b32_e64 v19, v19, v21, s[56:57]
	v_cndmask_b32_e64 v21, 0, v217, s[54:55]
	v_sub_f32_e32 v19, v19, v21
	v_sub_f32_e32 v19, v20, v19
	v_add_co_u32_e64 v20, s[54:55], s4, v6
	v_add_f32_e32 v22, v22, v19
	s_nop 0
	v_addc_co_u32_e64 v21, s[54:55], 0, v7, s[54:55]
	v_mov_b32_e32 v20, v82
	s_mov_b32 s4, 0xc713000
	s_waitcnt vmcnt(0)
	v_lshlrev_b32_e32 v20, 16, v20
	v_add_f32_e32 v20, v18, v20
	v_min_f32_e32 v21, 0, v20
	v_mul_f32_e64 v20, |v20|, s89
	v_exp_f32_e32 v20, v20
	s_nop 0
	v_add_f32_e32 v20, 1.0, v20
	v_cmp_gt_f32_e64 s[54:55], s20, v20
	s_nop 1
	v_cndmask_b32_e64 v23, 0, 32, s[54:55]
	v_ldexp_f32 v20, v20, v23
	v_log_f32_e32 v20, v20
	s_nop 0
	v_mul_f32_e32 v23, 0x3f317217, v20
	v_fma_f32 v23, v20, s21, -v23
	v_fmac_f32_e32 v23, 0x3377d1cf, v20
	v_fmac_f32_e32 v23, 0x3f317217, v20
	v_cmp_lt_f32_e64 s[56:57], |v20|, s8
	s_nop 1
	v_cndmask_b32_e64 v20, v20, v23, s[56:57]
	v_cndmask_b32_e64 v23, 0, v217, s[54:55]
	v_sub_f32_e32 v20, v20, v23
	v_sub_f32_e32 v20, v21, v20
	v_add_f32_e32 v24, v22, v20
	v_add_co_u32_e64 v22, s[54:55], s4, v6
	s_mov_b32 s4, 0xc719000
	s_nop 0
	v_addc_co_u32_e64 v23, s[54:55], 0, v7, s[54:55]
	v_mov_b32_e32 v21, v83
	s_waitcnt vmcnt(0)
	v_lshlrev_b32_e32 v21, 16, v21
	v_add_f32_e32 v21, v18, v21
	v_min_f32_e32 v22, 0, v21
	v_mul_f32_e64 v21, |v21|, s89
	v_exp_f32_e32 v21, v21
	s_nop 0
	v_add_f32_e32 v21, 1.0, v21
	v_cmp_gt_f32_e64 s[54:55], s20, v21
	s_nop 1
	v_cndmask_b32_e64 v23, 0, 32, s[54:55]
	v_ldexp_f32 v21, v21, v23
	v_log_f32_e32 v21, v21
	s_nop 0
	v_mul_f32_e32 v23, 0x3f317217, v21
	v_fma_f32 v23, v21, s21, -v23
	v_fmac_f32_e32 v23, 0x3377d1cf, v21
	v_fmac_f32_e32 v23, 0x3f317217, v21
	v_cmp_lt_f32_e64 s[56:57], |v21|, s8
	s_nop 1
	v_cndmask_b32_e64 v21, v21, v23, s[56:57]
	v_cndmask_b32_e64 v23, 0, v217, s[54:55]
	v_sub_f32_e32 v21, v21, v23
	v_sub_f32_e32 v21, v22, v21
	v_add_co_u32_e64 v22, s[54:55], s4, v6
	v_add_f32_e32 v24, v24, v21
	s_nop 0
	v_addc_co_u32_e64 v23, s[54:55], 0, v7, s[54:55]
	v_mov_b32_e32 v22, v84
	s_mov_b32 s4, 0xc71f000
	s_waitcnt vmcnt(0)
; __device__ __forceinline__ float bf1(bf16_t h) { return __uint_as_float(((unsigned)h) << 16); }
; __device__ __forceinline__ void fox_cumsum(const bf16_t* PROJ, const float* bforget, float* Carr, LAS unsigned char* lds, int bid, int G, int tid) {
;     ...
;         for (int i = 0; i < 8; ++i) { const float x = bf1(src[(size_t)i * NP]) + bf; lf[i] = fminf(x, 0.f) - __logf(1.f + __expf(-fabsf(x))); loc += lf[i]; }
;         float inc = loc;
; #pragma unroll
;         for (int o = 1; o < 64; o <<= 1) { const float y = __shfl_up(inc, o); if (lane >= o) inc += y; }
;         if (lane == 63) wt[wave] = inc;
;         __syncthreads();
;         float run = inc - loc;
;         for (int w2 = 0; w2 < wave; ++w2) run += wt[w2];
	v_lshlrev_b32_e32 v22, 16, v22
	v_add_f32_e32 v22, v18, v22
	v_min_f32_e32 v23, 0, v22
	v_mul_f32_e64 v22, |v22|, s89
	v_exp_f32_e32 v22, v22
	s_nop 0
	v_add_f32_e32 v22, 1.0, v22
	v_cmp_gt_f32_e64 s[54:55], s20, v22
	s_nop 1
	v_cndmask_b32_e64 v25, 0, 32, s[54:55]
	v_ldexp_f32 v22, v22, v25
	v_log_f32_e32 v22, v22
	s_nop 0
	v_mul_f32_e32 v25, 0x3f317217, v22
	v_fma_f32 v25, v22, s21, -v25
	v_fmac_f32_e32 v25, 0x3377d1cf, v22
	v_fmac_f32_e32 v25, 0x3f317217, v22
	v_cmp_lt_f32_e64 s[56:57], |v22|, s8
	s_nop 1
	v_cndmask_b32_e64 v22, v22, v25, s[56:57]
	v_cndmask_b32_e64 v25, 0, v217, s[54:55]
	v_sub_f32_e32 v22, v22, v25
	v_sub_f32_e32 v22, v23, v22
	v_add_f32_e32 v26, v24, v22
	v_add_co_u32_e64 v24, s[54:55], s4, v6
	s_mov_b32 s4, 0xc725000
	s_nop 0
	v_addc_co_u32_e64 v25, s[54:55], 0, v7, s[54:55]
	v_mov_b32_e32 v23, v85
	s_waitcnt vmcnt(0)
	v_lshlrev_b32_e32 v23, 16, v23
	v_add_f32_e32 v23, v18, v23
	v_min_f32_e32 v24, 0, v23
	v_mul_f32_e64 v23, |v23|, s89
	v_exp_f32_e32 v23, v23
	s_nop 0
	v_add_f32_e32 v23, 1.0, v23
	v_cmp_gt_f32_e64 s[54:55], s20, v23
	s_nop 1
	v_cndmask_b32_e64 v25, 0, 32, s[54:55]
	v_ldexp_f32 v23, v23, v25
	v_log_f32_e32 v23, v23
	s_nop 0
	v_mul_f32_e32 v25, 0x3f317217, v23
	v_fma_f32 v25, v23, s21, -v25
	v_fmac_f32_e32 v25, 0x3377d1cf, v23
	v_fmac_f32_e32 v25, 0x3f317217, v23
	v_cmp_lt_f32_e64 s[56:57], |v23|, s8
	s_nop 1
	v_cndmask_b32_e64 v23, v23, v25, s[56:57]
	v_cndmask_b32_e64 v25, 0, v217, s[54:55]
	v_sub_f32_e32 v23, v23, v25
	v_sub_f32_e32 v23, v24, v23
	v_add_co_u32_e64 v24, s[54:55], s4, v6
	s_mov_b32 s4, 0xc72a000
	s_nop 0
	v_addc_co_u32_e64 v25, s[54:55], 0, v7, s[54:55]
	v_mov_b32_e32 v24, v86
	v_add_f32_e32 v26, v26, v23
	s_waitcnt vmcnt(0)
	v_lshlrev_b32_e32 v24, 16, v24
	v_add_f32_e32 v24, v18, v24
	v_min_f32_e32 v25, 0, v24
	v_mul_f32_e64 v24, |v24|, s89
	v_exp_f32_e32 v24, v24
	s_nop 0
	v_add_f32_e32 v24, 1.0, v24
	v_cmp_gt_f32_e64 s[54:55], s20, v24
	s_nop 1
	v_cndmask_b32_e64 v27, 0, 32, s[54:55]
	v_ldexp_f32 v24, v24, v27
	v_log_f32_e32 v24, v24
	s_nop 0
	v_mul_f32_e32 v27, 0x3f317217, v24
	v_fma_f32 v27, v24, s21, -v27
	v_fmac_f32_e32 v27, 0x3377d1cf, v24
	v_fmac_f32_e32 v27, 0x3f317217, v24
	v_cmp_lt_f32_e64 s[56:57], |v24|, s8
	s_nop 1
	v_cndmask_b32_e64 v24, v24, v27, s[56:57]
	v_cndmask_b32_e64 v27, 0, v217, s[54:55]
	v_add_co_u32_e64 v6, s[54:55], s4, v6
	v_sub_f32_e32 v24, v24, v27
	s_nop 0
	v_addc_co_u32_e64 v7, s[54:55], 0, v7, s[54:55]
	v_mov_b32_e32 v6, v87
	v_sub_f32_e32 v24, v25, v24
	v_add_f32_e32 v25, v26, v24
	s_waitcnt vmcnt(0)
	v_lshlrev_b32_e32 v6, 16, v6
	v_add_f32_e32 v6, v18, v6
	v_min_f32_e32 v7, 0, v6
	v_mul_f32_e64 v6, |v6|, s89
	v_exp_f32_e32 v6, v6
	s_nop 0
	v_add_f32_e32 v6, 1.0, v6
	v_cmp_gt_f32_e64 s[54:55], s20, v6
	s_nop 1
	v_cndmask_b32_e64 v18, 0, 32, s[54:55]
	v_ldexp_f32 v6, v6, v18
	v_log_f32_e32 v6, v6
	s_nop 0
	v_mul_f32_e32 v18, 0x3f317217, v6
	v_fma_f32 v18, v6, s21, -v18
	v_fmac_f32_e32 v18, 0x3377d1cf, v6
	v_fmac_f32_e32 v18, 0x3f317217, v6
	v_cmp_lt_f32_e64 s[56:57], |v6|, s8
	s_nop 1
	v_cndmask_b32_e64 v6, v6, v18, s[56:57]
	v_cndmask_b32_e64 v18, 0, v217, s[54:55]
	v_sub_f32_e32 v6, v6, v18
	v_sub_f32_e32 v6, v7, v6
	v_add_f32_e32 v7, v25, v6
	ds_bpermute_b32 v18, v11, v7
	s_waitcnt lgkmcnt(0)
	v_add_f32_e32 v18, v7, v18
	v_cndmask_b32_e64 v18, v18, v7, s[38:39]
	ds_bpermute_b32 v25, v12, v18
	s_waitcnt lgkmcnt(0)
	v_add_f32_e32 v25, v18, v25
	v_cndmask_b32_e64 v18, v25, v18, s[42:43]
	ds_bpermute_b32 v25, v13, v18
	s_waitcnt lgkmcnt(0)
	v_add_f32_e32 v25, v18, v25
	v_cndmask_b32_e64 v18, v25, v18, s[44:45]
	ds_bpermute_b32 v25, v14, v18
	s_waitcnt lgkmcnt(0)
	v_add_f32_e32 v25, v18, v25
	v_cndmask_b32_e64 v18, v25, v18, s[46:47]
	ds_bpermute_b32 v25, v15, v18
	s_waitcnt lgkmcnt(0)
	v_add_f32_e32 v25, v18, v25
	v_cndmask_b32_e64 v18, v25, v18, s[48:49]
	ds_bpermute_b32 v25, v16, v18
	s_waitcnt lgkmcnt(0)
	v_add_f32_e32 v25, v18, v25
	s_and_saveexec_b64 s[54:55], vcc
	ds_write_b32 v10, v25
	s_or_b64 exec, exec, s[54:55]
	v_cndmask_b32_e64 v18, v25, v18, s[50:51]
	v_sub_f32_e32 v7, v18, v7
	s_waitcnt lgkmcnt(0)
	s_barrier
	s_and_saveexec_b64 s[56:57], s[40:41]
	s_cbranch_execz .LBB0_370
	s_mov_b32 s4, 0
	s_mov_b64 s[86:87], 0
	v_mov_b32_e32 v18, v9
